# w13->w2 boundary: 8-workgroup group barrier (workgroups sharing a GEMM row block, verified at run time to sit on one XCD) instead of the grid barrier
# speedup vs baseline: 1.0109x; 1.0019x over previous
_Z4mega6Paramsii:
	s_add_u32 s4, s0, 0x298
	v_writelane_b32 v252, s0, 0
	s_addc_u32 s5, s1, 0
	v_and_b32_e32 v196, 0x3ff, v0
	v_writelane_b32 v252, s1, 1
	v_writelane_b32 v252, s4, 2
	s_nop 1
	v_writelane_b32 v252, s5, 3
	v_cmp_eq_u32_e64 s[4:5], 0, v196
	s_mov_b64 s[0:1], exec
	s_nop 0
	v_writelane_b32 v252, s4, 4
	s_nop 1
	v_writelane_b32 v252, s5, 5
	s_and_b64 s[4:5], s[0:1], s[4:5]
	s_mov_b64 exec, s[4:5]
	v_mov_b32_e32 v2, 0
	v_mov_b32_e32 v3, v2
	v_mov_b32_e32 v4, v2
	v_mov_b32_e32 v5, v2
	ds_write_b128 v2, v[2:5]
	s_or_b64 exec, exec, s[0:1]
	v_readlane_b32 s0, v252, 0
	v_readlane_b32 s1, v252, 1
	s_load_dwordx2 s[34:35], s[0:1], 0x298
	s_nop 0
	s_load_dwordx2 s[0:1], s[0:1], 0x270
	s_waitcnt lgkmcnt(0)
	s_barrier
	v_writelane_b32 v252, s0, 6
	s_nop 1
	v_writelane_b32 v252, s1, 7
	s_getreg_b32 s0, hwreg(HW_REG_XCC_ID, 0, 4)
	s_and_b32 s3, s0, 15
	s_mov_b64 s[0:1], exec
	v_readlane_b32 s4, v252, 4
	v_readlane_b32 s5, v252, 5
	s_and_b64 s[4:5], s[0:1], s[4:5]
	s_mov_b64 exec, s[4:5]
	s_cbranch_execz .LBB0_5
	s_mov_b64 s[4:5], exec
	v_mbcnt_lo_u32_b32 v1, s4, 0
	v_mbcnt_hi_u32_b32 v1, s5, v1
	v_cmp_eq_u32_e32 vcc, 0, v1
	s_and_b64 s[6:7], exec, vcc
	s_mov_b64 exec, s[6:7]
	s_cbranch_execz .LBB0_5
	s_bcnt1_i32_b64 s4, s[4:5]
	s_lshl_b32 s6, s3, 8
	v_mov_b32_e32 v2, s4
	v_readlane_b32 s4, v252, 6
	v_mov_b32_e32 v1, s6
	v_readlane_b32 s5, v252, 7
	s_nop 4
	global_atomic_add v1, v2, s[4:5] offset:1024
	s_mul_i32 s6, s3, s3
	s_lshl_b32 s6, s6, 16
	s_or_b32 s6, s6, s3
	v_mov_b32_e32 v4, s6
	s_and_b32 s7, s2, 31
	s_lshl_b32 s7, s7, 4
	s_add_u32 s7, s7, 0x3800
	v_mov_b32_e32 v3, s7
	s_nop 1
	global_atomic_add v3, v4, s[4:5]

.LBB0_6:
	v_readlane_b32 s20, v252, 0
	v_readlane_b32 s21, v252, 1
	s_add_u32 s0, s20, 0x208
	s_load_dwordx16 s[56:71], s[20:21], 0x130
	s_addc_u32 s1, s21, 0
	v_writelane_b32 v252, s0, 10
	s_load_dwordx16 s[36:51], s[20:21], 0x170
	v_lshrrev_b32_e32 v1, 20, v0
	v_writelane_b32 v252, s1, 11
	s_add_u32 s0, s20, 0x200
	s_addc_u32 s1, s21, 0
	v_writelane_b32 v252, s0, 12
	s_waitcnt lgkmcnt(0)
	s_cmp_lg_u64 s[70:71], 0
	s_cselect_b64 s[4:5], -1, 0
	v_writelane_b32 v252, s1, 13
	v_writelane_b32 v252, s4, 14
	s_load_dword s1, s[20:21], 0x2a0
	s_mul_i32 s0, s35, s34
	v_writelane_b32 v252, s5, 15
	s_add_u32 s4, s36, 0x3000000
	s_addc_u32 s5, s37, 0
	v_writelane_b32 v252, s4, 16
	s_waitcnt lgkmcnt(0)
	s_mul_i32 s90, s0, s1
	v_lshrrev_b32_e32 v0, 10, v0
	v_writelane_b32 v252, s5, 17
	s_add_u32 s4, s36, 0x2000000
	s_addc_u32 s5, s37, 0
	v_writelane_b32 v252, s4, 18
	v_or_b32_e32 v0, v0, v1
	v_mov_b32_e32 v1, 0
	v_writelane_b32 v252, s5, 19
	v_mbcnt_lo_u32_b32 v2, -1, 0
	v_readlane_b32 s4, v252, 6
	v_readlane_b32 s5, v252, 7
	s_add_u32 s0, s4, 0x200
	s_addc_u32 s1, s5, 0
	v_writelane_b32 v252, s0, 20
	v_mov_b32_e32 v197, 0x358637bd
	v_mov_b32_e32 v200, 0x3000
	v_writelane_b32 v252, s1, 21
	s_add_u32 s0, s4, 0x1000
	s_addc_u32 s1, s5, 0
	v_writelane_b32 v252, s0, 22
	v_mov_b32_e32 v201, 0x6000
	v_mov_b32_e32 v202, 0x3a27c5ac
	v_writelane_b32 v252, s1, 23
	s_add_u32 s0, s4, 0x1100
	s_addc_u32 s1, s5, 0
	v_writelane_b32 v252, s0, 24
	v_mov_b32_e32 v204, 0x260
	v_mov_b32_e32 v206, 0x3c0881c4
	v_writelane_b32 v252, s1, 25
	s_add_u32 s0, s4, 0x1200
	s_addc_u32 s1, s5, 0
	v_writelane_b32 v252, s0, 26
	v_mov_b32_e32 v207, 0xbab64f3b
	v_mbcnt_hi_u32_b32 v209, -1, v2
	v_writelane_b32 v252, s1, 27
	s_add_u32 s0, s4, 0x1300
	s_addc_u32 s1, s5, 0
	v_writelane_b32 v252, s0, 28
	s_cmp_eq_u32 s3, 15
	v_mov_b32_e32 v210, v1
	v_writelane_b32 v252, s1, 29
	s_cselect_b64 s[0:1], -1, 0
	v_writelane_b32 v252, s0, 30
	s_cmp_eq_u32 s3, 14
	v_mov_b32_e32 v211, v1
	v_writelane_b32 v252, s1, 31
	s_cselect_b64 s[0:1], -1, 0
	v_writelane_b32 v252, s0, 32
	s_cmp_eq_u32 s3, 13
	v_mov_b32_e32 v212, v1
	v_writelane_b32 v252, s1, 33
	s_cselect_b64 s[0:1], -1, 0
	v_writelane_b32 v252, s0, 34
	s_cmp_eq_u32 s3, 12
	v_mov_b32_e32 v213, v1
	v_writelane_b32 v252, s1, 35
	s_cselect_b64 s[0:1], -1, 0
	v_writelane_b32 v252, s0, 36
	s_cmp_eq_u32 s3, 11
	v_mov_b32_e32 v208, 0xfffffd80
	v_writelane_b32 v252, s1, 37
	s_cselect_b64 s[0:1], -1, 0
	v_writelane_b32 v252, s0, 38
	s_cmp_eq_u32 s3, 10
	v_mov_b32_e32 v203, 0xfffffce0
	v_writelane_b32 v252, s1, 39
	s_cselect_b64 s[0:1], -1, 0
	v_writelane_b32 v252, s0, 40
	s_cmp_eq_u32 s3, 9
	v_mov_b32_e32 v223, 0xfffffc40
	v_writelane_b32 v252, s1, 41
	s_cselect_b64 s[0:1], -1, 0
	v_writelane_b32 v252, s0, 42
	s_cmp_eq_u32 s3, 8
	v_mov_b32_e32 v229, 0xfffffb50
	v_writelane_b32 v252, s1, 43
	s_cselect_b64 s[0:1], -1, 0
	v_writelane_b32 v252, s0, 44
	s_cmp_eq_u32 s3, 7
	v_mov_b32_e32 v230, 0xfffffb00
	v_writelane_b32 v252, s1, 45
	s_cselect_b64 s[0:1], -1, 0
	v_writelane_b32 v252, s0, 46
	s_cmp_eq_u32 s3, 6
	v_mov_b32_e32 v205, 0xfffff9c0
	v_writelane_b32 v252, s1, 47
	s_cselect_b64 s[0:1], -1, 0
	v_writelane_b32 v252, s0, 48
	s_cmp_eq_u32 s3, 5
	v_mov_b32_e32 v198, 0x7f800000
	v_writelane_b32 v252, s1, 49
	s_cselect_b64 s[0:1], -1, 0
	v_writelane_b32 v252, s0, 50
	s_cmp_eq_u32 s3, 4
	v_mov_b32_e32 v199, 0x100
	v_writelane_b32 v252, s1, 51
	s_cselect_b64 s[0:1], -1, 0
	v_writelane_b32 v252, s0, 52
	s_cmp_eq_u32 s3, 3
	v_mov_b32_e32 v250, 0x41b17218
	v_writelane_b32 v252, s1, 53
	s_cselect_b64 s[0:1], -1, 0
	v_writelane_b32 v252, s0, 54
	s_cmp_eq_u32 s3, 2
	v_mov_b32_e32 v251, 0x1c00
	v_writelane_b32 v252, s1, 55
	s_cselect_b64 s[0:1], -1, 0
	v_writelane_b32 v252, s0, 56
	s_cmp_eq_u32 s3, 1
	v_mov_b32_e32 v222, 0x800
	v_writelane_b32 v252, s1, 57
	s_cselect_b64 s[0:1], -1, 0
	v_writelane_b32 v252, s0, 58
	s_cmp_eq_u32 s3, 0
	v_not_b32_e32 v224, 63
	v_writelane_b32 v252, s1, 59
	s_cselect_b64 s[0:1], -1, 0
	v_writelane_b32 v252, s0, 60
	v_not_b32_e32 v225, 31
	v_mov_b32_e32 v226, 0xffc00000
	v_writelane_b32 v252, s1, 61
	s_lshl_b32 s0, s3, 8
	s_add_u32 s0, s4, s0
	s_addc_u32 s1, s5, 0
	s_add_u32 s6, s0, 0x1400
	s_addc_u32 s7, s1, 0
	s_add_u32 s0, s0, 0x2400
	s_addc_u32 s1, s1, 0
	v_writelane_b32 v253, s0, 0
	v_writelane_b32 v252, s6, 62
	v_mov_b32_e32 v227, 0x7fc00000
	v_writelane_b32 v253, s1, 1
	s_add_u32 s0, s4, 0x3400
	s_addc_u32 s1, s5, 0
	v_writelane_b32 v253, s0, 2
	v_writelane_b32 v252, s7, 63
	v_mov_b32_e32 v228, 0x900
	v_writelane_b32 v253, s1, 3
	s_add_u32 s0, s4, 0x3500
	s_addc_u32 s1, s5, 0
	v_writelane_b32 v253, s0, 4
	s_mov_b32 s3, 0x2aaaaaab
	s_mov_b32 s96, 0x3c000
	v_writelane_b32 v253, s1, 5
	s_movk_i32 s0, 0x3ff
	v_and_or_b32 v0, v0, s0, v196
	s_load_dwordx2 s[0:1], s[20:21], 0x288
	s_load_dwordx4 s[4:7], s[20:21], 0x278
	s_movk_i32 s93, 0x1f8
	s_mov_b32 s35, 0x18000
	s_mov_b32 s97, 0x54000
	s_mov_b32 s31, 0
	s_waitcnt lgkmcnt(0)
	s_add_u32 s8, s6, 0x80000
	v_writelane_b32 v253, s4, 6
	s_addc_u32 s9, s7, 0
	s_nop 0
	v_writelane_b32 v253, s5, 7
	v_writelane_b32 v253, s6, 8
	v_writelane_b32 v253, s7, 9
	v_writelane_b32 v253, s8, 10
	s_add_u32 s4, s62, 0x100000
	s_addc_u32 s5, s63, 0
	v_writelane_b32 v253, s9, 11
	v_writelane_b32 v253, s4, 12
	s_nop 1
	v_writelane_b32 v253, s5, 13
	s_add_u32 s4, s42, 8
	v_writelane_b32 v253, s36, 14
	s_addc_u32 s5, s43, 0
	s_nop 0
	v_writelane_b32 v253, s37, 15
	v_writelane_b32 v253, s38, 16
	v_writelane_b32 v253, s39, 17
	v_writelane_b32 v253, s40, 18
	v_writelane_b32 v253, s41, 19
	v_writelane_b32 v253, s42, 20
	v_writelane_b32 v253, s43, 21
	v_writelane_b32 v253, s44, 22
	v_writelane_b32 v253, s45, 23
	v_writelane_b32 v253, s46, 24
	v_writelane_b32 v253, s47, 25
	v_writelane_b32 v253, s48, 26
	v_writelane_b32 v253, s49, 27
	v_writelane_b32 v253, s50, 28
	v_writelane_b32 v253, s51, 29
	v_writelane_b32 v253, s4, 30
	s_mov_b32 s36, 0xc000
	s_mov_b32 s39, 0x3e8293ee
	v_writelane_b32 v253, s5, 31
	s_add_u32 s4, s0, 0x2400
	v_writelane_b32 v253, s0, 32
	s_addc_u32 s5, s1, 0
	s_mov_b32 s38, 0x42000
	v_writelane_b32 v253, s1, 33
	v_writelane_b32 v253, s4, 34
	s_mov_b32 s37, 0x4ec4ec4f
	s_nop 0
	v_writelane_b32 v253, s5, 35
	s_load_dwordx8 s[4:11], s[20:21], 0x230
	s_waitcnt lgkmcnt(0)
	s_add_u32 s0, s4, 0x800
	v_writelane_b32 v253, s4, 36
	s_addc_u32 s1, s5, 0
	s_nop 0
	v_writelane_b32 v253, s5, 37
	v_writelane_b32 v253, s6, 38
	v_writelane_b32 v253, s7, 39
	v_writelane_b32 v253, s8, 40
	v_writelane_b32 v253, s9, 41
	v_writelane_b32 v253, s10, 42
	v_writelane_b32 v253, s11, 43
	s_load_dwordx16 s[4:19], s[20:21], 0x1f0
	v_writelane_b32 v253, s0, 44
	s_nop 1
	v_writelane_b32 v253, s1, 45
	s_waitcnt lgkmcnt(0)
	s_add_u32 s0, s16, 0x1000
	v_writelane_b32 v253, s4, 46
	s_addc_u32 s1, s17, 0
	s_nop 0
	v_writelane_b32 v253, s5, 47
	v_writelane_b32 v253, s6, 48
	v_writelane_b32 v253, s7, 49
	v_writelane_b32 v253, s8, 50
	v_writelane_b32 v253, s9, 51
	v_writelane_b32 v253, s10, 52
	v_writelane_b32 v253, s11, 53
	v_writelane_b32 v253, s12, 54
	v_writelane_b32 v253, s13, 55
	v_writelane_b32 v253, s14, 56
	v_writelane_b32 v253, s15, 57
	v_writelane_b32 v253, s16, 58
	v_writelane_b32 v253, s17, 59
	v_writelane_b32 v253, s18, 60
	v_writelane_b32 v253, s19, 61
	s_load_dwordx16 s[4:19], s[20:21], 0x1b0
	v_writelane_b32 v253, s0, 62
	s_nop 1
	v_writelane_b32 v253, s1, 63
	s_waitcnt lgkmcnt(0)
	s_add_u32 s0, s14, 0x200
	v_writelane_b32 v254, s4, 0
	s_addc_u32 s1, s15, 0
	s_nop 0
	v_writelane_b32 v254, s5, 1
	v_writelane_b32 v254, s6, 2
	v_writelane_b32 v254, s7, 3
	v_writelane_b32 v254, s8, 4
	v_writelane_b32 v254, s9, 5
	v_writelane_b32 v254, s10, 6
	v_writelane_b32 v254, s11, 7
	v_writelane_b32 v254, s12, 8
	v_writelane_b32 v254, s13, 9
	v_writelane_b32 v254, s14, 10
	v_writelane_b32 v254, s15, 11
	v_writelane_b32 v254, s16, 12
	v_writelane_b32 v254, s17, 13
	v_writelane_b32 v254, s18, 14
	v_writelane_b32 v254, s19, 15
	v_writelane_b32 v254, s0, 16
	s_load_dwordx4 s[4:7], s[20:21], 0x250
	s_nop 0
	v_writelane_b32 v254, s1, 17
	s_add_i32 s0, 16, 0x14000
	v_writelane_b32 v254, s0, 18
	v_readlane_b32 s0, v252, 8
	v_readlane_b32 s1, v252, 9
	s_mov_b32 s30, s0
	v_cmp_eq_u32_e64 s[0:1], 0, v0
	s_nop 1
	v_writelane_b32 v254, s0, 19
	s_nop 1
	v_writelane_b32 v254, s1, 20
	s_load_dwordx2 s[0:1], s[20:21], 0x260
	s_load_dwordx8 s[8:15], s[20:21], 0x0
	s_load_dwordx16 s[40:55], s[20:21], 0x30
	s_load_dwordx16 s[72:87], s[20:21], 0xf0
	s_waitcnt lgkmcnt(0)
	v_writelane_b32 v254, s0, 21
	s_nop 1
	v_writelane_b32 v254, s1, 22
	v_writelane_b32 v254, s4, 23
	s_nop 1
	v_writelane_b32 v254, s5, 24
	v_writelane_b32 v254, s6, 25
	v_writelane_b32 v254, s7, 26
	v_writelane_b32 v254, s40, 27
	s_nop 1
	v_writelane_b32 v254, s41, 28
	v_writelane_b32 v254, s42, 29
	v_writelane_b32 v254, s43, 30
	v_writelane_b32 v254, s44, 31
	v_writelane_b32 v254, s45, 32
	v_writelane_b32 v254, s46, 33
	v_writelane_b32 v254, s47, 34
	v_writelane_b32 v254, s48, 35
	v_writelane_b32 v254, s49, 36
	v_writelane_b32 v254, s50, 37
	v_writelane_b32 v254, s51, 38
	v_writelane_b32 v254, s52, 39
	v_writelane_b32 v254, s53, 40
	v_writelane_b32 v254, s54, 41
	v_writelane_b32 v254, s55, 42
	s_load_dwordx16 s[40:55], s[20:21], 0xb0
	s_waitcnt lgkmcnt(0)
	v_writelane_b32 v254, s40, 43
	s_nop 1
	v_writelane_b32 v254, s41, 44
	v_writelane_b32 v254, s42, 45
	v_writelane_b32 v254, s43, 46
	v_writelane_b32 v254, s44, 47
	v_writelane_b32 v254, s45, 48
	v_writelane_b32 v254, s46, 49
	v_writelane_b32 v254, s47, 50
	v_writelane_b32 v254, s48, 51
	v_writelane_b32 v254, s49, 52
	v_writelane_b32 v254, s50, 53
	v_writelane_b32 v254, s51, 54
	v_writelane_b32 v254, s52, 55
	v_writelane_b32 v254, s53, 56
	v_writelane_b32 v254, s54, 57
	v_writelane_b32 v254, s55, 58
	s_load_dwordx16 s[40:55], s[20:21], 0x70
	s_waitcnt lgkmcnt(0)
	v_writelane_b32 v254, s40, 59
	s_nop 1
	v_writelane_b32 v255, s45, 0
	v_writelane_b32 v255, s46, 1
	v_writelane_b32 v255, s47, 2
	v_writelane_b32 v255, s48, 3
	v_writelane_b32 v255, s49, 4
	v_writelane_b32 v255, s50, 5
	v_writelane_b32 v255, s51, 6
	v_writelane_b32 v255, s52, 7
	v_writelane_b32 v255, s53, 8
	v_writelane_b32 v255, s54, 9
	v_writelane_b32 v255, s55, 10
	v_writelane_b32 v255, s90, 11
	v_writelane_b32 v255, s8, 12
	v_writelane_b32 v254, s41, 60
	v_writelane_b32 v254, s42, 61
	v_writelane_b32 v255, s9, 13
	v_writelane_b32 v255, s10, 14
	v_writelane_b32 v255, s11, 15
	v_writelane_b32 v255, s12, 16
	v_writelane_b32 v255, s13, 17
	v_writelane_b32 v254, s43, 62
	v_writelane_b32 v255, s14, 18
	v_writelane_b32 v254, s44, 63
	v_writelane_b32 v255, s15, 19
	v_writelane_b32 v255, 0, 45
	v_writelane_b32 v255, 0, 30
	s_mov_b32 s0, 1
	s_nop 0
	v_writelane_b32 v255, s0, 31
	s_branch .LBB0_11

.LBB0_11:
	s_cmp_eq_u32 s30, 1
	s_cbranch_scc0 .Lgb_c1
	v_readlane_b32 s4, v252, 6
	v_readlane_b32 s5, v252, 7
	s_and_b32 s0, s2, 31
	s_lshl_b32 s0, s0, 4
	s_add_u32 s0, s0, 0x3800
	v_mov_b32_e32 v2, s0
	s_nop 3
	global_load_dword v2, v2, s[4:5] sc1
	s_waitcnt vmcnt(0)
	v_readfirstlane_b32 s0, v2
	s_and_b32 s1, s0, 0xffff
	s_lshr_b32 s0, s0, 16
	s_lshl_b32 s0, s0, 3
	s_mul_i32 s1, s1, s1
	s_cmp_eq_u32 s0, s1
	s_cbranch_scc1 .Lgb_c1
	v_mov_b32_e32 v2, 1
	v_mov_b32_e32 v3, 0x3a00
	global_atomic_add v3, v2, s[4:5]
	s_waitcnt vmcnt(0)
.Lgb_c1:
	s_cmp_eq_u32 s30, 2
	s_cbranch_scc0 .Lgb_c2
	v_readlane_b32 s4, v252, 6
	v_readlane_b32 s5, v252, 7
	v_mov_b32_e32 v2, 0x3a00
	s_nop 4
	global_load_dword v2, v2, s[4:5] sc1
	s_waitcnt vmcnt(0)
	v_readfirstlane_b32 s0, v2
	s_min_u32 s0, s0, 1
	s_nop 0
	v_writelane_b32 v255, s0, 31

.LBB0_1135:
	v_readlane_b32 s0, v252, 8
	v_readlane_b32 s1, v252, 9
	s_cmp_lg_u32 s4, s0
	s_mov_b64 s[0:1], -1
	s_cbranch_scc0 .LBB0_1189
	v_readlane_b32 s0, v255, 20
	v_readlane_b32 s1, v255, 31
	s_mov_b32 s4, 0x8020400
	s_mov_b32 s5, 0x4
	s_lshr_b64 s[4:5], s[4:5], s0
	s_andn2_b32 s4, s4, s1
	s_bitcmp1_b32 s4, 0
	s_cbranch_scc0 .Lgb_grid
	v_readlane_b32 s6, v255, 30
	s_add_i32 s6, s6, 1
	s_nop 0
	v_writelane_b32 v255, s6, 30
	s_waitcnt vmcnt(0) lgkmcnt(0)
	s_barrier
	s_mov_b64 s[0:1], exec
	v_readlane_b32 s20, v252, 4
	v_readlane_b32 s21, v252, 5
	s_and_b64 s[20:21], s[0:1], s[20:21]
	s_mov_b64 exec, s[20:21]
	s_cbranch_execz .LBB0_1188
	v_readlane_b32 s4, v252, 6
	v_readlane_b32 s5, v252, 7
	s_and_b32 s7, s2, 31
	s_lshl_b32 s7, s7, 4
	s_add_u32 s7, s7, 0x3600
	v_mov_b32_e32 v2, s7
	v_mov_b32_e32 v3, 1
	s_lshl_b32 s6, s6, 3
	s_nop 1
	global_atomic_add v2, v3, s[4:5]
	buffer_inv sc1
	s_mov_b32 s7, 0
.Lgb_poll:
	global_load_dword v3, v2, s[4:5] sc1
	s_waitcnt vmcnt(0)
	v_readfirstlane_b32 s20, v3
	s_cmp_ge_u32 s20, s6
	s_cbranch_scc1 .LBB0_1188
	s_sleep 1
	s_add_i32 s7, s7, 1
	s_cmp_lt_u32 s7, 0x100000
	s_cbranch_scc1 .Lgb_poll
	s_branch .LBB0_1188
.Lgb_grid:
	s_waitcnt vmcnt(0)
	s_waitcnt lgkmcnt(0)
	s_barrier
	s_mov_b64 s[0:1], exec
	v_readlane_b32 s20, v252, 4
	v_readlane_b32 s21, v252, 5
	s_and_b64 s[20:21], s[0:1], s[20:21]
	s_mov_b64 exec, s[20:21]
	s_cbranch_execz .LBB0_1188
	s_waitcnt vmcnt(0) expcnt(0) lgkmcnt(0)
	ds_read_b32 v3, v1
	ds_read_b32 v2, v1 offset:4
	s_waitcnt lgkmcnt(1)
	v_cmp_ne_u32_e32 vcc, 0, v3
	s_cbranch_vccnz .LBB0_1152
	s_mov_b32 s26, 1
	s_branch .LBB0_1140
